# p2 compress-MLP first GEMM: operands loaded row-coalesced (4 rows x 256 B per instruction) and staged through a padded per-wave LDS image instead of 32-row x 32-B gather loads; same MFMA order
# speedup vs baseline: 1.0239x; 1.0151x over previous
; #define P_biask  WSP(float, WS_BIASK)
; #define P_biasv  WSP(float, WS_BIASV)
; DI int opaque_tid() { int t = threadIdx.x; asm volatile("" : "+v"(t)); return t; }
; #define MFMA32(a, b, c) __builtin_amdgcn_mfma_f32_32x32x16_bf16((a), (b), (c), 0, 0, 0)
; DI void compress_item(const Params& P, unsigned char* smem, int item) {
;     const int tid = opaque_tid(), lane = tid & 63, wave = tid >> 6, l32 = lane & 31, hh = lane >> 5;
;     const int ct = item & 3, g = (item >> 2) & 1, b = (item >> 3) & 15, which = item >> 7;
;     const int nt = wave & 3, kh = wave >> 2;
;     const bf16_t* src = P_proj + (size_t)b * TT * LDP + (which ? C_VCMP : C_KCMP) + g * 128;
;     const bf16_t* w1T = which ? P_w1vT : P_w1kT; const bf16_t* w2T = which ? P_w2vT : P_w2kT; const float* bias = which ? P_biasv : P_biask;
;     float* red = (float*)smem;
;     bf16_t* hid = (bf16_t*)(smem + 16384);
;     float* outf = (float*)(smem + 32768);
;     int crow_a = ct * 32 + l32; if (crow_a > 126) crow_a = 126;
;     f32x16 acc;
; #pragma unroll
;     for (int i = 0; i < 16; ++i) acc[i] = 0.f;
; #pragma unroll 4
;     for (int l = 16 * kh; l < 16 * kh + 16; ++l) {
;         const bf16_t* arow = src + (size_t)(16 * crow_a + l) * LDP; const bf16_t* brow = w1T + (size_t)(32 * nt + l32) * 4096 + l * 128;
; #pragma unroll
;         for (int ks = 0; ks < 8; ++ks) { const bf16x8 a = *(const bf16x8*)(arow + 16 * ks + 8 * hh), bb = *(const bf16x8*)(brow + 16 * ks + 8 * hh); acc = MFMA32(a, bb, acc); }
.LBB0_253:
	s_andn2_b64 vcc, exec, s[2:3]
	s_cbranch_vccnz .LBB0_271
	s_bfe_u32 s0, s76, 0x40003
	s_mul_i32 s71, s0, 0x3b00000
	s_lshl_b32 s0, s77, 1
	s_and_b32 s73, s0, 0x100
	s_add_i32 s58, s96, 0xfffffb00
	s_cmpk_lt_u32 s58, 0x80
	s_cselect_b64 s[4:5], -1, 0
	s_cmpk_gt_u32 s58, 0x7f
	s_cselect_b64 s[2:3], -1, 0
	s_and_b64 s[0:1], s[4:5], exec
	s_movk_i32 s0, 0x3800
	s_cselect_b32 s74, s0, 0x3a00
	s_lshl_b32 s72, s58, 5
	s_and_b32 s33, s72, 0x60
	s_and_b64 s[0:1], s[4:5], exec
	v_mov_b32_e32 v24, v215
	s_mov_b32 s0, 0x3eb00000
	s_cselect_b32 s0, s0, 0x3ec00000
	v_and_b32_e32 v25, 31, v24
	v_or_b32_e32 v2, s33, v25
	v_mov_b32_e32 v0, s0
	s_movk_i32 s0, 0x7f
	v_cmp_ne_u32_e32 vcc, s0, v2
	s_add_u32 s0, s30, s74
	s_addc_u32 s1, s31, 0
	s_add_u32 s0, s0, s73
	s_addc_u32 s1, s1, 0
	v_lshlrev_b32_e32 v3, 4, v2
	s_add_u32 s0, s0, s71
	v_ashrrev_i32_e32 v28, 8, v24
	v_cndmask_b32_e32 v2, v183, v3, vcc
	v_lshrrev_b32_e32 v3, 1, v24
	s_addc_u32 s1, s1, 0
	v_and_b32_e32 v64, 16, v3
	v_lshl_add_u32 v4, v28, 4, v2
	v_mov_b64_e32 v[2:3], s[0:1]
	v_mad_i64_i32 v[16:17], s[0:1], v4, s83, v[2:3]
	v_bfe_u32 v254, v24, 4, 2
	v_and_b32_e32 v255, 15, v24
	v_lshlrev_b32_e32 v170, 4, v255
	v_mov_b32_e32 v171, 0
	s_add_i32 s70, s33, 0
	v_add_u32_e32 v172, s70, v254
	v_min_u32_e32 v172, 0x7e, v172
	v_lshlrev_b32_e32 v172, 4, v172
	v_lshl_add_u32 v172, v28, 4, v172
	v_mad_i64_i32 v[216:217], s[70:71], v172, s83, v[2:3]
	v_lshl_add_u64 v[216:217], v[216:217], 0, v[170:171]
	s_add_i32 s70, s33, 4
	v_add_u32_e32 v172, s70, v254
	v_min_u32_e32 v172, 0x7e, v172
	v_lshlrev_b32_e32 v172, 4, v172
	v_lshl_add_u32 v172, v28, 4, v172
	v_mad_i64_i32 v[218:219], s[70:71], v172, s83, v[2:3]
	v_lshl_add_u64 v[218:219], v[218:219], 0, v[170:171]
	s_add_i32 s70, s33, 8
	v_add_u32_e32 v172, s70, v254
	v_min_u32_e32 v172, 0x7e, v172
	v_lshlrev_b32_e32 v172, 4, v172
	v_lshl_add_u32 v172, v28, 4, v172
	v_mad_i64_i32 v[220:221], s[70:71], v172, s83, v[2:3]
	v_lshl_add_u64 v[220:221], v[220:221], 0, v[170:171]
	s_add_i32 s70, s33, 12
	v_add_u32_e32 v172, s70, v254
	v_min_u32_e32 v172, 0x7e, v172
	v_lshlrev_b32_e32 v172, 4, v172
	v_lshl_add_u32 v172, v28, 4, v172
	v_mad_i64_i32 v[222:223], s[70:71], v172, s83, v[2:3]
	v_lshl_add_u64 v[222:223], v[222:223], 0, v[170:171]
	s_add_i32 s70, s33, 16
	v_add_u32_e32 v172, s70, v254
	v_min_u32_e32 v172, 0x7e, v172
	v_lshlrev_b32_e32 v172, 4, v172
	v_lshl_add_u32 v172, v28, 4, v172
	v_mad_i64_i32 v[224:225], s[70:71], v172, s83, v[2:3]
	v_lshl_add_u64 v[224:225], v[224:225], 0, v[170:171]
	s_add_i32 s70, s33, 20
	v_add_u32_e32 v172, s70, v254
	v_min_u32_e32 v172, 0x7e, v172
	v_lshlrev_b32_e32 v172, 4, v172
	v_lshl_add_u32 v172, v28, 4, v172
	v_mad_i64_i32 v[226:227], s[70:71], v172, s83, v[2:3]
	v_lshl_add_u64 v[226:227], v[226:227], 0, v[170:171]
	s_add_i32 s70, s33, 24
	v_add_u32_e32 v172, s70, v254
	v_min_u32_e32 v172, 0x7e, v172
	v_lshlrev_b32_e32 v172, 4, v172
	v_lshl_add_u32 v172, v28, 4, v172
	v_mad_i64_i32 v[228:229], s[70:71], v172, s83, v[2:3]
	v_lshl_add_u64 v[228:229], v[228:229], 0, v[170:171]
	s_add_i32 s70, s33, 28
	v_add_u32_e32 v172, s70, v254
	v_min_u32_e32 v172, 0x7e, v172
	v_lshlrev_b32_e32 v172, 4, v172
	v_lshl_add_u32 v172, v28, 4, v172
	v_mad_i64_i32 v[230:231], s[70:71], v172, s83, v[2:3]
	v_lshl_add_u64 v[230:231], v[230:231], 0, v[170:171]
	v_lshlrev_b32_e32 v2, 11, v28
	v_mov_b32_e32 v1, v65
	v_ashrrev_i32_e32 v3, 31, v2
	v_lshl_add_u64 v[0:1], v[2:3], 1, v[0:1]
	v_lshlrev_b32_e32 v2, 12, v24
	v_lshlrev_b32_e32 v3, 13, v25
	s_mov_b32 s0, 0xc0000
	v_and_or_b32 v2, v2, s0, v3
	v_mov_b32_e32 v3, v65
	v_lshl_add_u64 v[0:1], v[0:1], 0, v[2:3]
	v_lshl_add_u64 v[18:19], s[30:31], 0, v[0:1]
	v_mov_b32_e32 v0, 0
	v_lshrrev_b32_e32 v27, 5, v24
	v_lshrrev_b32_e32 v26, 6, v24
	s_mov_b32 s70, 16
	v_mov_b32_e32 v1, v0
	v_mov_b32_e32 v2, v0
	v_mov_b32_e32 v3, v0
	v_mov_b32_e32 v4, v0
	v_mov_b32_e32 v5, v0
	v_mov_b32_e32 v6, v0
	v_mov_b32_e32 v7, v0
	v_mov_b32_e32 v8, v0
	v_mov_b32_e32 v9, v0
	v_mov_b32_e32 v10, v0
	v_mov_b32_e32 v11, v0
	v_mov_b32_e32 v12, v0
	v_mov_b32_e32 v13, v0
	v_mov_b32_e32 v14, v0
	v_mov_b32_e32 v15, v0
	v_add_u32_e32 v172, 0, v254
	v_sub_u32_e32 v172, v172, v25
	v_lshlrev_b32_e32 v212, 13, v172
	v_add_u32_e32 v212, v212, v170
	v_ashrrev_i32_e32 v213, 31, v212
	v_lshl_add_u64 v[232:233], v[18:19], 0, v[212:213]
	v_add_u32_e32 v172, 4, v254
	v_sub_u32_e32 v172, v172, v25
	v_lshlrev_b32_e32 v212, 13, v172
	v_add_u32_e32 v212, v212, v170
	v_ashrrev_i32_e32 v213, 31, v212
	v_lshl_add_u64 v[234:235], v[18:19], 0, v[212:213]
	v_add_u32_e32 v172, 8, v254
	v_sub_u32_e32 v172, v172, v25
	v_lshlrev_b32_e32 v212, 13, v172
	v_add_u32_e32 v212, v212, v170
	v_ashrrev_i32_e32 v213, 31, v212
	v_lshl_add_u64 v[240:241], v[18:19], 0, v[212:213]
	v_add_u32_e32 v172, 12, v254
	v_sub_u32_e32 v172, v172, v25
	v_lshlrev_b32_e32 v212, 13, v172
	v_add_u32_e32 v212, v212, v170
	v_ashrrev_i32_e32 v213, 31, v212
	v_lshl_add_u64 v[242:243], v[18:19], 0, v[212:213]
	v_add_u32_e32 v172, 16, v254
	v_sub_u32_e32 v172, v172, v25
	v_lshlrev_b32_e32 v212, 13, v172
	v_add_u32_e32 v212, v212, v170
	v_ashrrev_i32_e32 v213, 31, v212
	v_lshl_add_u64 v[244:245], v[18:19], 0, v[212:213]
	v_add_u32_e32 v172, 20, v254
	v_sub_u32_e32 v172, v172, v25
	v_lshlrev_b32_e32 v212, 13, v172
	v_add_u32_e32 v212, v212, v170
	v_ashrrev_i32_e32 v213, 31, v212
	v_lshl_add_u64 v[246:247], v[18:19], 0, v[212:213]
	v_add_u32_e32 v172, 24, v254
	v_sub_u32_e32 v172, v172, v25
	v_lshlrev_b32_e32 v212, 13, v172
	v_add_u32_e32 v212, v212, v170
	v_ashrrev_i32_e32 v213, 31, v212
	v_lshl_add_u64 v[248:249], v[18:19], 0, v[212:213]
	v_add_u32_e32 v172, 28, v254
; #define MFMA32(a, b, c) __builtin_amdgcn_mfma_f32_32x32x16_bf16((a), (b), (c), 0, 0, 0)
; DI void compress_item(const Params& P, unsigned char* smem, int item) {
;     ...
;     for (int l = 16 * kh; l < 16 * kh + 16; ++l) {
;         const bf16_t* arow = src + (size_t)(16 * crow_a + l) * LDP; const bf16_t* brow = w1T + (size_t)(32 * nt + l32) * 4096 + l * 128;
; #pragma unroll
;         for (int ks = 0; ks < 8; ++ks) { const bf16x8 a = *(const bf16x8*)(arow + 16 * ks + 8 * hh), bb = *(const bf16x8*)(brow + 16 * ks + 8 * hh); acc = MFMA32(a, bb, acc); }
	v_sub_u32_e32 v172, v172, v25
	v_lshlrev_b32_e32 v212, 13, v172
	v_add_u32_e32 v212, v212, v170
	v_ashrrev_i32_e32 v213, 31, v212
	v_lshl_add_u64 v[250:251], v[18:19], 0, v[212:213]
	v_mul_u32_u24_e32 v172, 0x4400, v26
	v_mul_u32_u24_e32 v212, 0x110, v254
	v_add3_u32 v252, v212, v172, v170
	v_mul_u32_u24_e32 v212, 0x110, v25
	v_add_u32_e32 v253, v212, v172
	v_bfe_u32 v255, v24, 5, 1
	v_lshl_add_u32 v253, v255, 4, v253
	s_mov_b64 s[70:71], 0x7600
	s_mov_b64 s[74:75], 0x100
	global_load_dwordx4 v[68:71], v[216:217], off
	global_load_dwordx4 v[100:103], v[232:233], off
	global_load_dwordx4 v[72:75], v[218:219], off
	global_load_dwordx4 v[104:107], v[234:235], off
	global_load_dwordx4 v[76:79], v[220:221], off
	global_load_dwordx4 v[108:111], v[240:241], off
	global_load_dwordx4 v[80:83], v[222:223], off
	global_load_dwordx4 v[112:115], v[242:243], off
	global_load_dwordx4 v[84:87], v[224:225], off
	global_load_dwordx4 v[116:119], v[244:245], off
	global_load_dwordx4 v[88:91], v[226:227], off
	global_load_dwordx4 v[120:123], v[246:247], off
	global_load_dwordx4 v[92:95], v[228:229], off
	global_load_dwordx4 v[124:127], v[248:249], off
	global_load_dwordx4 v[96:99], v[230:231], off
	global_load_dwordx4 v[128:131], v[250:251], off
	v_lshl_add_u64 v[216:217], v[216:217], 0, s[70:71]
	v_lshl_add_u64 v[232:233], v[232:233], 0, s[74:75]
	v_lshl_add_u64 v[218:219], v[218:219], 0, s[70:71]
	v_lshl_add_u64 v[234:235], v[234:235], 0, s[74:75]
	v_lshl_add_u64 v[220:221], v[220:221], 0, s[70:71]
	v_lshl_add_u64 v[240:241], v[240:241], 0, s[74:75]
	v_lshl_add_u64 v[222:223], v[222:223], 0, s[70:71]
	v_lshl_add_u64 v[242:243], v[242:243], 0, s[74:75]
	v_lshl_add_u64 v[224:225], v[224:225], 0, s[70:71]
	v_lshl_add_u64 v[244:245], v[244:245], 0, s[74:75]
	v_lshl_add_u64 v[226:227], v[226:227], 0, s[70:71]
	v_lshl_add_u64 v[246:247], v[246:247], 0, s[74:75]
	v_lshl_add_u64 v[228:229], v[228:229], 0, s[70:71]
	v_lshl_add_u64 v[248:249], v[248:249], 0, s[74:75]
	v_lshl_add_u64 v[230:231], v[230:231], 0, s[70:71]
	v_lshl_add_u64 v[250:251], v[250:251], 0, s[74:75]
	global_load_dwordx4 v[132:135], v[216:217], off
	global_load_dwordx4 v[166:169], v[232:233], off
	global_load_dwordx4 v[136:139], v[218:219], off
	global_load_dwordx4 v[174:177], v[234:235], off
	global_load_dwordx4 v[140:143], v[220:221], off
	global_load_dwordx4 v[188:191], v[240:241], off
	global_load_dwordx4 v[144:147], v[222:223], off
	global_load_dwordx4 v[192:195], v[242:243], off
	global_load_dwordx4 v[148:151], v[224:225], off
	global_load_dwordx4 v[196:199], v[244:245], off
	global_load_dwordx4 v[154:157], v[226:227], off
	global_load_dwordx4 v[200:203], v[246:247], off
	global_load_dwordx4 v[158:161], v[228:229], off
	global_load_dwordx4 v[204:207], v[248:249], off
	global_load_dwordx4 v[162:165], v[230:231], off
	global_load_dwordx4 v[208:211], v[250:251], off
	v_lshl_add_u64 v[216:217], v[216:217], 0, s[70:71]
	v_lshl_add_u64 v[232:233], v[232:233], 0, s[74:75]
	v_lshl_add_u64 v[218:219], v[218:219], 0, s[70:71]
	v_lshl_add_u64 v[234:235], v[234:235], 0, s[74:75]
	v_lshl_add_u64 v[220:221], v[220:221], 0, s[70:71]
	v_lshl_add_u64 v[240:241], v[240:241], 0, s[74:75]
	v_lshl_add_u64 v[222:223], v[222:223], 0, s[70:71]
	v_lshl_add_u64 v[242:243], v[242:243], 0, s[74:75]
	v_lshl_add_u64 v[224:225], v[224:225], 0, s[70:71]
	v_lshl_add_u64 v[244:245], v[244:245], 0, s[74:75]
	v_lshl_add_u64 v[226:227], v[226:227], 0, s[70:71]
	v_lshl_add_u64 v[246:247], v[246:247], 0, s[74:75]
	v_lshl_add_u64 v[228:229], v[228:229], 0, s[70:71]
	v_lshl_add_u64 v[248:249], v[248:249], 0, s[74:75]
	v_lshl_add_u64 v[230:231], v[230:231], 0, s[70:71]
	v_lshl_add_u64 v[250:251], v[250:251], 0, s[74:75]
	s_mov_b32 s73, 0
.LBB0_255:
	s_waitcnt vmcnt(16)
	ds_write_b128 v252, v[68:71]
	ds_write_b128 v252, v[100:103] offset:8704
	ds_write_b128 v252, v[72:75] offset:1088
	ds_write_b128 v252, v[104:107] offset:9792
	ds_write_b128 v252, v[76:79] offset:2176
	ds_write_b128 v252, v[108:111] offset:10880
	ds_write_b128 v252, v[80:83] offset:3264
	ds_write_b128 v252, v[112:115] offset:11968
	ds_write_b128 v252, v[84:87] offset:4352
	ds_write_b128 v252, v[116:119] offset:13056
	ds_write_b128 v252, v[88:91] offset:5440
	ds_write_b128 v252, v[120:123] offset:14144
	ds_write_b128 v252, v[92:95] offset:6528
	ds_write_b128 v252, v[124:127] offset:15232
	ds_write_b128 v252, v[96:99] offset:7616
	ds_write_b128 v252, v[128:131] offset:16320
	s_cmp_ge_u32 s73, 14
	s_cbranch_scc1 .Lcmpnp0
	global_load_dwordx4 v[68:71], v[216:217], off
	global_load_dwordx4 v[100:103], v[232:233], off
	global_load_dwordx4 v[72:75], v[218:219], off
	global_load_dwordx4 v[104:107], v[234:235], off
	global_load_dwordx4 v[76:79], v[220:221], off
	global_load_dwordx4 v[108:111], v[240:241], off
	global_load_dwordx4 v[80:83], v[222:223], off
	global_load_dwordx4 v[112:115], v[242:243], off
	global_load_dwordx4 v[84:87], v[224:225], off
	global_load_dwordx4 v[116:119], v[244:245], off
	global_load_dwordx4 v[88:91], v[226:227], off
	global_load_dwordx4 v[120:123], v[246:247], off
	global_load_dwordx4 v[92:95], v[228:229], off
	global_load_dwordx4 v[124:127], v[248:249], off
	global_load_dwordx4 v[96:99], v[230:231], off
	global_load_dwordx4 v[128:131], v[250:251], off
	v_lshl_add_u64 v[216:217], v[216:217], 0, s[70:71]
	v_lshl_add_u64 v[232:233], v[232:233], 0, s[74:75]
	v_lshl_add_u64 v[218:219], v[218:219], 0, s[70:71]
	v_lshl_add_u64 v[234:235], v[234:235], 0, s[74:75]
	v_lshl_add_u64 v[220:221], v[220:221], 0, s[70:71]
	v_lshl_add_u64 v[240:241], v[240:241], 0, s[74:75]
	v_lshl_add_u64 v[222:223], v[222:223], 0, s[70:71]
	v_lshl_add_u64 v[242:243], v[242:243], 0, s[74:75]
	v_lshl_add_u64 v[224:225], v[224:225], 0, s[70:71]
	v_lshl_add_u64 v[244:245], v[244:245], 0, s[74:75]
	v_lshl_add_u64 v[226:227], v[226:227], 0, s[70:71]
	v_lshl_add_u64 v[246:247], v[246:247], 0, s[74:75]
	v_lshl_add_u64 v[228:229], v[228:229], 0, s[70:71]
	v_lshl_add_u64 v[248:249], v[248:249], 0, s[74:75]
	v_lshl_add_u64 v[230:231], v[230:231], 0, s[70:71]
	v_lshl_add_u64 v[250:251], v[250:251], 0, s[74:75]
; #define MFMA32(a, b, c) __builtin_amdgcn_mfma_f32_32x32x16_bf16((a), (b), (c), 0, 0, 0)
; DI void compress_item(const Params& P, unsigned char* smem, int item) {
;     ...
; #pragma unroll 4
;     for (int l = 16 * kh; l < 16 * kh + 16; ++l) {
;         const bf16_t* arow = src + (size_t)(16 * crow_a + l) * LDP; const bf16_t* brow = w1T + (size_t)(32 * nt + l32) * 4096 + l * 128;
; #pragma unroll
;         for (int ks = 0; ks < 8; ++ks) { const bf16x8 a = *(const bf16x8*)(arow + 16 * ks + 8 * hh), bb = *(const bf16x8*)(brow + 16 * ks + 8 * hh); acc = MFMA32(a, bb, acc); }
;     }
;     __syncthreads();
;     if (kh == 1) {
; #pragma unroll
;         for (int i = 0; i < 16; ++i) red[(nt * 64 + lane) * 16 + i] = acc[i]; }
.Lcmpnp0:
	s_waitcnt lgkmcnt(0)
	ds_read_b128 v[36:39], v253
	ds_read_b128 v[52:55], v253 offset:8704
	ds_read_b128 v[40:43], v253 offset:32
	ds_read_b128 v[56:59], v253 offset:8736
	ds_read_b128 v[44:47], v253 offset:64
	ds_read_b128 v[60:63], v253 offset:8768
	ds_read_b128 v[48:51], v253 offset:96
	ds_read_b128 v[20:23], v253 offset:8800
	s_waitcnt lgkmcnt(6)
	v_mfma_f32_32x32x16_bf16 v[0:15], v[36:39], v[52:55], v[0:15]
	s_waitcnt lgkmcnt(4)
	v_mfma_f32_32x32x16_bf16 v[0:15], v[40:43], v[56:59], v[0:15]
	s_waitcnt lgkmcnt(2)
	v_mfma_f32_32x32x16_bf16 v[0:15], v[44:47], v[60:63], v[0:15]
	s_waitcnt lgkmcnt(0)
	v_mfma_f32_32x32x16_bf16 v[0:15], v[48:51], v[20:23], v[0:15]
	ds_read_b128 v[36:39], v253 offset:128
	ds_read_b128 v[52:55], v253 offset:8832
	ds_read_b128 v[40:43], v253 offset:160
	ds_read_b128 v[56:59], v253 offset:8864
	ds_read_b128 v[44:47], v253 offset:192
	ds_read_b128 v[60:63], v253 offset:8896
	ds_read_b128 v[48:51], v253 offset:224
	ds_read_b128 v[20:23], v253 offset:8928
	s_waitcnt lgkmcnt(6)
	v_mfma_f32_32x32x16_bf16 v[0:15], v[36:39], v[52:55], v[0:15]
	s_waitcnt lgkmcnt(4)
	v_mfma_f32_32x32x16_bf16 v[0:15], v[40:43], v[56:59], v[0:15]
	s_waitcnt lgkmcnt(2)
	v_mfma_f32_32x32x16_bf16 v[0:15], v[44:47], v[60:63], v[0:15]
	s_waitcnt lgkmcnt(0)
	v_mfma_f32_32x32x16_bf16 v[0:15], v[48:51], v[20:23], v[0:15]
	s_cmp_lt_u32 s73, 14
	s_cbranch_scc1 .Lcmpw1
	s_waitcnt vmcnt(0)
	s_branch .Lcmpw1d
.Lcmpw1:
	s_waitcnt vmcnt(16)
.Lcmpw1d:
	ds_write_b128 v252, v[132:135]
	ds_write_b128 v252, v[166:169] offset:8704
	ds_write_b128 v252, v[136:139] offset:1088
	ds_write_b128 v252, v[174:177] offset:9792
	ds_write_b128 v252, v[140:143] offset:2176
	ds_write_b128 v252, v[188:191] offset:10880
	ds_write_b128 v252, v[144:147] offset:3264
	ds_write_b128 v252, v[192:195] offset:11968
	ds_write_b128 v252, v[148:151] offset:4352
	ds_write_b128 v252, v[196:199] offset:13056
	ds_write_b128 v252, v[154:157] offset:5440
	ds_write_b128 v252, v[200:203] offset:14144
	ds_write_b128 v252, v[158:161] offset:6528
	ds_write_b128 v252, v[204:207] offset:15232
	ds_write_b128 v252, v[162:165] offset:7616
	ds_write_b128 v252, v[208:211] offset:16320
	s_cmp_ge_u32 s73, 14
	s_cbranch_scc1 .Lcmpnp1
	global_load_dwordx4 v[132:135], v[216:217], off
	global_load_dwordx4 v[166:169], v[232:233], off
	global_load_dwordx4 v[136:139], v[218:219], off
	global_load_dwordx4 v[174:177], v[234:235], off
	global_load_dwordx4 v[140:143], v[220:221], off
	global_load_dwordx4 v[188:191], v[240:241], off
	global_load_dwordx4 v[144:147], v[222:223], off
	global_load_dwordx4 v[192:195], v[242:243], off
	global_load_dwordx4 v[148:151], v[224:225], off
	global_load_dwordx4 v[196:199], v[244:245], off
	global_load_dwordx4 v[154:157], v[226:227], off
	global_load_dwordx4 v[200:203], v[246:247], off
	global_load_dwordx4 v[158:161], v[228:229], off
	global_load_dwordx4 v[204:207], v[248:249], off
	global_load_dwordx4 v[162:165], v[230:231], off
	global_load_dwordx4 v[208:211], v[250:251], off
	v_lshl_add_u64 v[216:217], v[216:217], 0, s[70:71]
	v_lshl_add_u64 v[232:233], v[232:233], 0, s[74:75]
	v_lshl_add_u64 v[218:219], v[218:219], 0, s[70:71]
	v_lshl_add_u64 v[234:235], v[234:235], 0, s[74:75]
	v_lshl_add_u64 v[220:221], v[220:221], 0, s[70:71]
	v_lshl_add_u64 v[240:241], v[240:241], 0, s[74:75]
	v_lshl_add_u64 v[222:223], v[222:223], 0, s[70:71]
	v_lshl_add_u64 v[242:243], v[242:243], 0, s[74:75]
	v_lshl_add_u64 v[224:225], v[224:225], 0, s[70:71]
	v_lshl_add_u64 v[244:245], v[244:245], 0, s[74:75]
	v_lshl_add_u64 v[226:227], v[226:227], 0, s[70:71]
	v_lshl_add_u64 v[246:247], v[246:247], 0, s[74:75]
	v_lshl_add_u64 v[228:229], v[228:229], 0, s[70:71]
	v_lshl_add_u64 v[248:249], v[248:249], 0, s[74:75]
	v_lshl_add_u64 v[230:231], v[230:231], 0, s[70:71]
	v_lshl_add_u64 v[250:251], v[250:251], 0, s[74:75]
.Lcmpnp1:
	s_waitcnt lgkmcnt(0)
	ds_read_b128 v[36:39], v253
	ds_read_b128 v[52:55], v253 offset:8704
	ds_read_b128 v[40:43], v253 offset:32
	ds_read_b128 v[56:59], v253 offset:8736
	ds_read_b128 v[44:47], v253 offset:64
	ds_read_b128 v[60:63], v253 offset:8768
	ds_read_b128 v[48:51], v253 offset:96
	ds_read_b128 v[20:23], v253 offset:8800
	s_waitcnt lgkmcnt(6)
	v_mfma_f32_32x32x16_bf16 v[0:15], v[36:39], v[52:55], v[0:15]
	s_waitcnt lgkmcnt(4)
	v_mfma_f32_32x32x16_bf16 v[0:15], v[40:43], v[56:59], v[0:15]
	s_waitcnt lgkmcnt(2)
	v_mfma_f32_32x32x16_bf16 v[0:15], v[44:47], v[60:63], v[0:15]
	s_waitcnt lgkmcnt(0)
	v_mfma_f32_32x32x16_bf16 v[0:15], v[48:51], v[20:23], v[0:15]
	ds_read_b128 v[36:39], v253 offset:128
	ds_read_b128 v[52:55], v253 offset:8832
	ds_read_b128 v[40:43], v253 offset:160
	ds_read_b128 v[56:59], v253 offset:8864
	ds_read_b128 v[44:47], v253 offset:192
	ds_read_b128 v[60:63], v253 offset:8896
	ds_read_b128 v[48:51], v253 offset:224
	ds_read_b128 v[20:23], v253 offset:8928
	s_waitcnt lgkmcnt(6)
	v_mfma_f32_32x32x16_bf16 v[0:15], v[36:39], v[52:55], v[0:15]
	s_waitcnt lgkmcnt(4)
	v_mfma_f32_32x32x16_bf16 v[0:15], v[40:43], v[56:59], v[0:15]
	s_waitcnt lgkmcnt(2)
	v_mfma_f32_32x32x16_bf16 v[0:15], v[44:47], v[60:63], v[0:15]
	s_waitcnt lgkmcnt(0)
	v_mfma_f32_32x32x16_bf16 v[0:15], v[48:51], v[20:23], v[0:15]
	s_add_i32 s73, s73, 2
	s_cmp_lt_u32 s73, 16
	s_cbranch_scc1 .LBB0_255
	v_cmp_eq_u32_e32 vcc, 1, v28
	s_barrier
	s_and_saveexec_b64 s[70:71], vcc
	s_cbranch_execz .LBB0_258
	v_lshlrev_b32_e32 v16, 6, v24
	v_and_b32_e32 v16, 0x3fc0, v16
	v_add_u32_e32 v16, 0, v16
	s_nop 3
	ds_write_b128 v16, v[0:3]
	ds_write_b128 v16, v[4:7] offset:16
	ds_write_b128 v16, v[8:11] offset:32
	ds_write_b128 v16, v[12:15] offset:48
